# EpiUp: conv/bias weight loads and their address arithmetic hoisted in front of the align barrier (overlap the wait for the trailing half)
# speedup vs baseline: 1.1119x; 1.0025x over previous
.Lpeel_p8:
	s_add_i32 s51, 0, 0x18000
	s_add_i32 s52, 0, 0x1c000
	v_add_u32_e32 v140, s51, v191
	v_add_u32_e32 v156, s52, v191
	ds_read_b128 v[116:119], v140
	ds_read_b128 v[120:123], v140 offset:1024
	ds_read_b128 v[124:127], v140 offset:2048
	ds_read_b128 v[140:143], v140 offset:3072
	ds_read_b128 v[144:147], v156
	ds_read_b128 v[148:151], v156 offset:1024
	ds_read_b128 v[152:155], v156 offset:2048
	ds_read_b128 v[156:159], v156 offset:3072
	s_add_u32 s28, s28, 0x40000
	s_addc_u32 s29, s29, 0
	s_mov_b32 m0, s39
	v_lshl_add_u64 v[222:223], s[28:29], 0, v[164:165]
	ds_read_b128 v[170:173], v193 offset:32768
	ds_read_b128 v[176:179], v193 offset:33792
	ds_read_b128 v[180:183], v193 offset:34816
	ds_read_b128 v[184:187], v193 offset:35840
	ds_read_b128 v[194:197], v193 offset:36864
	ds_read_b128 v[198:201], v193 offset:37888
	ds_read_b128 v[202:205], v193 offset:38912
	ds_read_b128 v[212:215], v193 offset:39936
	global_load_lds_dwordx4 v[222:223], off
	v_lshl_add_u64 v[222:223], s[28:29], 0, v[162:163]
	s_mov_b32 m0, s40
	s_nop 0
	global_load_lds_dwordx4 v[222:223], off
	s_waitcnt vmcnt(8)
	s_waitcnt lgkmcnt(0)
	s_barrier
	s_waitcnt lgkmcnt(0)
	v_mfma_f32_16x16x32_bf16 v[136:139], v[116:119], v[170:173], v[136:139]
	v_mfma_f32_16x16x32_bf16 v[92:95], v[124:127], v[170:173], v[92:95]
	v_mfma_f32_16x16x32_bf16 v[132:135], v[116:119], v[180:183], v[132:135]
	v_mfma_f32_16x16x32_bf16 v[88:91], v[124:127], v[180:183], v[88:91]
	v_mfma_f32_16x16x32_bf16 v[112:115], v[116:119], v[194:197], v[112:115]
	v_mfma_f32_16x16x32_bf16 v[80:83], v[124:127], v[194:197], v[80:83]
	v_mfma_f32_16x16x32_bf16 v[104:107], v[116:119], v[202:205], v[104:107]
	v_mfma_f32_16x16x32_bf16 v[72:75], v[124:127], v[202:205], v[72:75]
	v_mfma_f32_16x16x32_bf16 v[136:139], v[120:123], v[176:179], v[136:139]
	v_mfma_f32_16x16x32_bf16 v[92:95], v[140:143], v[176:179], v[92:95]
	v_mfma_f32_16x16x32_bf16 v[132:135], v[120:123], v[184:187], v[132:135]
	v_mfma_f32_16x16x32_bf16 v[88:91], v[140:143], v[184:187], v[88:91]
	v_mfma_f32_16x16x32_bf16 v[112:115], v[120:123], v[198:201], v[112:115]
	v_mfma_f32_16x16x32_bf16 v[80:83], v[140:143], v[198:201], v[80:83]
	v_mfma_f32_16x16x32_bf16 v[104:107], v[120:123], v[212:215], v[104:107]
	v_mfma_f32_16x16x32_bf16 v[72:75], v[140:143], v[212:215], v[72:75]
	v_mfma_f32_16x16x32_bf16 v[128:131], v[144:147], v[170:173], v[128:131]
	v_mfma_f32_16x16x32_bf16 v[84:87], v[152:155], v[170:173], v[84:87]
	v_mfma_f32_16x16x32_bf16 v[108:111], v[144:147], v[180:183], v[108:111]
	v_mfma_f32_16x16x32_bf16 v[76:79], v[152:155], v[180:183], v[76:79]
	v_mfma_f32_16x16x32_bf16 v[100:103], v[144:147], v[194:197], v[100:103]
	v_mfma_f32_16x16x32_bf16 v[68:71], v[152:155], v[194:197], v[68:71]
	v_mfma_f32_16x16x32_bf16 v[96:99], v[144:147], v[202:205], v[96:99]
	v_mfma_f32_16x16x32_bf16 v[64:67], v[152:155], v[202:205], v[64:67]
	v_mfma_f32_16x16x32_bf16 v[128:131], v[148:151], v[176:179], v[128:131]
	v_mfma_f32_16x16x32_bf16 v[84:87], v[156:159], v[176:179], v[84:87]
	v_mfma_f32_16x16x32_bf16 v[108:111], v[148:151], v[184:187], v[108:111]
	v_mfma_f32_16x16x32_bf16 v[76:79], v[156:159], v[184:187], v[76:79]
	v_mfma_f32_16x16x32_bf16 v[100:103], v[148:151], v[198:201], v[100:103]
	v_mfma_f32_16x16x32_bf16 v[68:71], v[156:159], v[198:201], v[68:71]
	v_mfma_f32_16x16x32_bf16 v[96:99], v[148:151], v[212:215], v[96:99]
	v_mfma_f32_16x16x32_bf16 v[64:67], v[156:159], v[212:215], v[64:67]
	s_barrier
	s_add_i32 s28, s51, s36
	v_lshl_add_u64 v[188:189], v[188:189], 0, s[74:75]
	s_mov_b32 m0, s28
	ds_read_b128 v[170:173], v193 offset:49152
	ds_read_b128 v[176:179], v193 offset:50176
	ds_read_b128 v[180:183], v193 offset:51200
	ds_read_b128 v[184:187], v193 offset:52224
	ds_read_b128 v[194:197], v193 offset:53248
	ds_read_b128 v[198:201], v193 offset:54272
	ds_read_b128 v[202:205], v193 offset:55296
	ds_read_b128 v[212:215], v193 offset:56320
	global_load_lds_dwordx4 v[188:189], off
	s_add_i32 m0, s28, 0x2000
	s_add_u32 s26, s26, 0x40080
	v_lshl_add_u64 v[188:189], v[216:217], 0, s[74:75]
	s_addc_u32 s27, s27, 0
	s_add_i32 s28, s52, s36
	global_load_lds_dwordx4 v[188:189], off
	v_lshl_add_u64 v[188:189], s[26:27], 0, v[168:169]
	s_mov_b32 m0, s28
	s_nop 0
	global_load_lds_dwordx4 v[188:189], off
	v_lshl_add_u64 v[188:189], s[26:27], 0, v[160:161]
	s_add_i32 m0, s28, 0x2000
	s_nop 0
	global_load_lds_dwordx4 v[188:189], off
	v_lshl_add_u64 v[188:189], v[218:219], 0, s[74:75]
	s_mov_b32 m0, s41
	s_nop 0
	global_load_lds_dwordx4 v[188:189], off
	v_lshl_add_u64 v[188:189], v[220:221], 0, s[74:75]
	s_mov_b32 m0, s42
	s_nop 0
	global_load_lds_dwordx4 v[188:189], off
	s_waitcnt vmcnt(8)
	s_waitcnt lgkmcnt(0)
	s_barrier
	s_waitcnt lgkmcnt(0)
	v_mfma_f32_16x16x32_bf16 v[60:63], v[116:119], v[170:173], v[60:63]
	v_mfma_f32_16x16x32_bf16 v[28:31], v[124:127], v[170:173], v[28:31]
	v_mfma_f32_16x16x32_bf16 v[56:59], v[116:119], v[180:183], v[56:59]
	v_mfma_f32_16x16x32_bf16 v[24:27], v[124:127], v[180:183], v[24:27]
	v_mfma_f32_16x16x32_bf16 v[48:51], v[116:119], v[194:197], v[48:51]
	v_mfma_f32_16x16x32_bf16 v[16:19], v[124:127], v[194:197], v[16:19]
	v_mfma_f32_16x16x32_bf16 v[40:43], v[116:119], v[202:205], v[40:43]
	v_mfma_f32_16x16x32_bf16 v[8:11], v[124:127], v[202:205], v[8:11]
	v_mfma_f32_16x16x32_bf16 v[60:63], v[120:123], v[176:179], v[60:63]
	v_mfma_f32_16x16x32_bf16 v[28:31], v[140:143], v[176:179], v[28:31]
	v_mfma_f32_16x16x32_bf16 v[56:59], v[120:123], v[184:187], v[56:59]
	v_mfma_f32_16x16x32_bf16 v[24:27], v[140:143], v[184:187], v[24:27]
	v_mfma_f32_16x16x32_bf16 v[48:51], v[120:123], v[198:201], v[48:51]
	v_mfma_f32_16x16x32_bf16 v[16:19], v[140:143], v[198:201], v[16:19]
	v_mfma_f32_16x16x32_bf16 v[40:43], v[120:123], v[212:215], v[40:43]
	v_mfma_f32_16x16x32_bf16 v[8:11], v[140:143], v[212:215], v[8:11]
	v_mfma_f32_16x16x32_bf16 v[52:55], v[144:147], v[170:173], v[52:55]
	v_mfma_f32_16x16x32_bf16 v[20:23], v[152:155], v[170:173], v[20:23]
	v_mfma_f32_16x16x32_bf16 v[44:47], v[144:147], v[180:183], v[44:47]
	v_mfma_f32_16x16x32_bf16 v[12:15], v[152:155], v[180:183], v[12:15]
	v_mfma_f32_16x16x32_bf16 v[36:39], v[144:147], v[194:197], v[36:39]
	v_mfma_f32_16x16x32_bf16 v[4:7], v[152:155], v[194:197], v[4:7]
	v_mfma_f32_16x16x32_bf16 v[32:35], v[144:147], v[202:205], v[32:35]
	v_mfma_f32_16x16x32_bf16 v[0:3], v[152:155], v[202:205], v[0:3]
	v_mfma_f32_16x16x32_bf16 v[52:55], v[148:151], v[176:179], v[52:55]
	v_mfma_f32_16x16x32_bf16 v[20:23], v[156:159], v[176:179], v[20:23]
	v_mfma_f32_16x16x32_bf16 v[44:47], v[148:151], v[184:187], v[44:47]
	v_mfma_f32_16x16x32_bf16 v[12:15], v[156:159], v[184:187], v[12:15]
	v_mfma_f32_16x16x32_bf16 v[36:39], v[148:151], v[198:201], v[36:39]
	v_mfma_f32_16x16x32_bf16 v[4:7], v[156:159], v[198:201], v[4:7]
	v_mfma_f32_16x16x32_bf16 v[32:35], v[148:151], v[212:215], v[32:35]
	v_mfma_f32_16x16x32_bf16 v[0:3], v[156:159], v[212:215], v[0:3]
	s_barrier
	s_add_i32 s50, s50, 2
	s_add_u32 s48, s48, 0x100
	s_addc_u32 s49, s49, 0
	s_add_u32 s24, s24, 0x100
	s_addc_u32 s25, s25, 0
	s_cmp_gt_u32 s50, 13
	s_cbranch_scc0 .LBB0_779
	v_lshl_or_b32 v184, s44, 7, v192
	v_ashrrev_i32_e32 v185, 31, v184
	v_lshlrev_b64 v[116:117], 2, v[184:185]
	v_lshl_add_u64 v[182:183], s[0:1], 0, v[116:117]
	v_lshl_add_u64 v[180:181], s[12:13], 0, v[116:117]
	v_lshl_add_u64 v[178:179], s[14:15], 0, v[116:117]
	v_lshl_add_u64 v[176:177], s[2:3], 0, v[116:117]
	global_load_dwordx4 v[140:143], v[182:183], off offset:16
	global_load_dwordx4 v[156:159], v[182:183], off
	global_load_dwordx4 v[116:119], v[180:181], off offset:16
	global_load_dwordx4 v[144:147], v[180:181], off
	global_load_dwordx4 v[120:123], v[178:179], off offset:16
	global_load_dwordx4 v[148:151], v[178:179], off
	global_load_dwordx4 v[124:127], v[176:177], off offset:16
	global_load_dwordx4 v[152:155], v[176:177], off
	s_and_b64 vcc, exec, s[10:11]
	s_cbranch_vccz .LBB0_782
	s_barrier
.LBB0_782:
	v_lshl_add_u32 v194, s45, 8, v190
	s_movk_i32 s17, 0xb00
	v_readlane_b32 s24, v253, 0
	v_readlane_b32 s25, v253, 1
	v_readlane_b32 s26, v253, 2
	v_readlane_b32 s27, v253, 3
	s_andn2_b64 vcc, exec, s[6:7]
	v_mul_lo_u32 v194, v194, s17
	v_mov_b32_e32 v188, 0xbfb8aa3b
	v_mov_b32_e32 v189, 0xbfb8aa3b
	v_add_lshl_u32 v194, v194, v184, 1
	v_mov_b32_dpp v172, v136 row_ror:1 row_mask:0xf bank_mask:0xf
	v_mov_b32_dpp v176, v132 row_ror:1 row_mask:0xf bank_mask:0xf
	v_mov_b32_dpp v178, v112 row_ror:1 row_mask:0xf bank_mask:0xf
	v_mov_b32_dpp v180, v132 row_ror:15 row_mask:0xf bank_mask:0xf
	v_mov_b32_dpp v182, v112 row_ror:15 row_mask:0xf bank_mask:0xf
	v_mov_b32_dpp v184, v104 row_ror:15 row_mask:0xf bank_mask:0xf
	v_mov_b32_dpp v173, v137 row_ror:1 row_mask:0xf bank_mask:0xf
	v_mov_b32_dpp v177, v133 row_ror:1 row_mask:0xf bank_mask:0xf
	v_mov_b32_dpp v179, v113 row_ror:1 row_mask:0xf bank_mask:0xf
	v_mov_b32_dpp v181, v133 row_ror:15 row_mask:0xf bank_mask:0xf
	v_mov_b32_dpp v183, v113 row_ror:15 row_mask:0xf bank_mask:0xf
	v_mov_b32_dpp v185, v105 row_ror:15 row_mask:0xf bank_mask:0xf
	v_mov_b32_dpp v170, v136 row_shr:1 row_mask:0xf bank_mask:0xf bound_ctrl:1
	v_mov_b32_dpp v172, v132 row_shr:1 row_mask:0xf bank_mask:0xf
	v_mov_b32_dpp v176, v112 row_shr:1 row_mask:0xf bank_mask:0xf
	v_mov_b32_dpp v178, v104 row_shr:1 row_mask:0xf bank_mask:0xf
	v_mov_b32_dpp v180, v136 row_shl:1 row_mask:0xf bank_mask:0xf
	v_mov_b32_dpp v182, v132 row_shl:1 row_mask:0xf bank_mask:0xf
	v_mov_b32_dpp v184, v112 row_shl:1 row_mask:0xf bank_mask:0xf
	v_mov_b32_dpp v186, v104 row_shl:1 row_mask:0xf bank_mask:0xf bound_ctrl:1
	v_mov_b32_dpp v171, v137 row_shr:1 row_mask:0xf bank_mask:0xf bound_ctrl:1
	v_mov_b32_dpp v173, v133 row_shr:1 row_mask:0xf bank_mask:0xf
	v_mov_b32_dpp v177, v113 row_shr:1 row_mask:0xf bank_mask:0xf
	v_mov_b32_dpp v179, v105 row_shr:1 row_mask:0xf bank_mask:0xf
	v_mov_b32_dpp v181, v137 row_shl:1 row_mask:0xf bank_mask:0xf
	v_mov_b32_dpp v183, v133 row_shl:1 row_mask:0xf bank_mask:0xf
	v_mov_b32_dpp v185, v113 row_shl:1 row_mask:0xf bank_mask:0xf
	v_mov_b32_dpp v187, v105 row_shl:1 row_mask:0xf bank_mask:0xf bound_ctrl:1
	s_waitcnt vmcnt(0)
	v_pk_fma_f32 v[170:171], v[170:171], v[156:157], v[152:153]
	v_pk_fma_f32 v[172:173], v[172:173], v[156:157], v[152:153]
	v_pk_fma_f32 v[176:177], v[176:177], v[156:157], v[152:153]
	v_pk_fma_f32 v[178:179], v[178:179], v[156:157], v[152:153]
	v_pk_fma_f32 v[170:171], v[136:137], v[144:145], v[170:171]
	v_pk_fma_f32 v[172:173], v[132:133], v[144:145], v[172:173]
	v_pk_fma_f32 v[176:177], v[112:113], v[144:145], v[176:177]
	v_pk_fma_f32 v[178:179], v[104:105], v[144:145], v[178:179]
	v_pk_fma_f32 v[170:171], v[180:181], v[148:149], v[170:171]
	v_pk_fma_f32 v[172:173], v[182:183], v[148:149], v[172:173]
	v_pk_fma_f32 v[176:177], v[184:185], v[148:149], v[176:177]
	v_pk_fma_f32 v[178:179], v[186:187], v[148:149], v[178:179]
	v_pk_mul_f32 v[180:181], v[170:171], v[188:189]
	v_pk_mul_f32 v[182:183], v[172:173], v[188:189]
	v_pk_mul_f32 v[184:185], v[176:177], v[188:189]
	v_pk_mul_f32 v[186:187], v[178:179], v[188:189]
	v_exp_f32_e32 v180, v180
	v_exp_f32_e32 v181, v181
	v_exp_f32_e32 v182, v182
	v_exp_f32_e32 v183, v183
	v_exp_f32_e32 v184, v184
	v_exp_f32_e32 v185, v185
	v_exp_f32_e32 v186, v186
	v_exp_f32_e32 v187, v187
	s_nop 0
	v_pk_add_f32 v[180:181], v[180:181], 1.0 op_sel_hi:[1,0]
	v_pk_add_f32 v[182:183], v[182:183], 1.0 op_sel_hi:[1,0]
	v_pk_add_f32 v[184:185], v[184:185], 1.0 op_sel_hi:[1,0]
	v_pk_add_f32 v[186:187], v[186:187], 1.0 op_sel_hi:[1,0]
	v_rcp_f32_e32 v180, v180
	v_rcp_f32_e32 v181, v181
	v_rcp_f32_e32 v182, v182
	v_rcp_f32_e32 v183, v183
	v_rcp_f32_e32 v184, v184
	v_rcp_f32_e32 v185, v185
	v_rcp_f32_e32 v186, v186
	v_rcp_f32_e32 v187, v187
	s_nop 0
	v_pk_mul_f32 v[136:137], v[170:171], v[180:181]
	v_pk_mul_f32 v[132:133], v[172:173], v[182:183]
	v_pk_mul_f32 v[112:113], v[176:177], v[184:185]
	v_pk_mul_f32 v[104:105], v[178:179], v[186:187]
	v_pk_mul_f32 v[136:137], v[136:137], v[128:129]
	v_pk_mul_f32 v[132:133], v[132:133], v[108:109]
	v_pk_mul_f32 v[112:113], v[112:113], v[100:101]
	v_pk_mul_f32 v[104:105], v[104:105], v[96:97]
	v_mov_b32_dpp v172, v138 row_ror:1 row_mask:0xf bank_mask:0xf
	v_mov_b32_dpp v176, v134 row_ror:1 row_mask:0xf bank_mask:0xf
	v_mov_b32_dpp v178, v114 row_ror:1 row_mask:0xf bank_mask:0xf
	v_mov_b32_dpp v180, v134 row_ror:15 row_mask:0xf bank_mask:0xf
	v_mov_b32_dpp v182, v114 row_ror:15 row_mask:0xf bank_mask:0xf
	v_mov_b32_dpp v184, v106 row_ror:15 row_mask:0xf bank_mask:0xf
	v_mov_b32_dpp v173, v139 row_ror:1 row_mask:0xf bank_mask:0xf
	v_mov_b32_dpp v177, v135 row_ror:1 row_mask:0xf bank_mask:0xf
	v_mov_b32_dpp v179, v115 row_ror:1 row_mask:0xf bank_mask:0xf
	v_mov_b32_dpp v181, v135 row_ror:15 row_mask:0xf bank_mask:0xf
	v_mov_b32_dpp v183, v115 row_ror:15 row_mask:0xf bank_mask:0xf
	v_mov_b32_dpp v185, v107 row_ror:15 row_mask:0xf bank_mask:0xf
	v_mov_b32_dpp v170, v138 row_shr:1 row_mask:0xf bank_mask:0xf bound_ctrl:1
	v_mov_b32_dpp v172, v134 row_shr:1 row_mask:0xf bank_mask:0xf
	v_mov_b32_dpp v176, v114 row_shr:1 row_mask:0xf bank_mask:0xf
	v_mov_b32_dpp v178, v106 row_shr:1 row_mask:0xf bank_mask:0xf
	v_mov_b32_dpp v180, v138 row_shl:1 row_mask:0xf bank_mask:0xf
	v_mov_b32_dpp v182, v134 row_shl:1 row_mask:0xf bank_mask:0xf
	v_mov_b32_dpp v184, v114 row_shl:1 row_mask:0xf bank_mask:0xf
	v_mov_b32_dpp v186, v106 row_shl:1 row_mask:0xf bank_mask:0xf bound_ctrl:1
	v_mov_b32_dpp v171, v139 row_shr:1 row_mask:0xf bank_mask:0xf bound_ctrl:1
	v_mov_b32_dpp v173, v135 row_shr:1 row_mask:0xf bank_mask:0xf
	v_mov_b32_dpp v177, v115 row_shr:1 row_mask:0xf bank_mask:0xf
	v_mov_b32_dpp v179, v107 row_shr:1 row_mask:0xf bank_mask:0xf
	v_mov_b32_dpp v181, v139 row_shl:1 row_mask:0xf bank_mask:0xf
	v_mov_b32_dpp v183, v135 row_shl:1 row_mask:0xf bank_mask:0xf
	v_mov_b32_dpp v185, v115 row_shl:1 row_mask:0xf bank_mask:0xf
	v_mov_b32_dpp v187, v107 row_shl:1 row_mask:0xf bank_mask:0xf bound_ctrl:1
	v_pk_fma_f32 v[170:171], v[170:171], v[158:159], v[154:155]
	v_pk_fma_f32 v[172:173], v[172:173], v[158:159], v[154:155]
	v_pk_fma_f32 v[176:177], v[176:177], v[158:159], v[154:155]
	v_pk_fma_f32 v[178:179], v[178:179], v[158:159], v[154:155]
	v_pk_fma_f32 v[170:171], v[138:139], v[146:147], v[170:171]
	v_pk_fma_f32 v[172:173], v[134:135], v[146:147], v[172:173]
	v_pk_fma_f32 v[176:177], v[114:115], v[146:147], v[176:177]
	v_pk_fma_f32 v[178:179], v[106:107], v[146:147], v[178:179]
	v_pk_fma_f32 v[170:171], v[180:181], v[150:151], v[170:171]
	v_pk_fma_f32 v[172:173], v[182:183], v[150:151], v[172:173]
	v_pk_fma_f32 v[176:177], v[184:185], v[150:151], v[176:177]
	v_pk_fma_f32 v[178:179], v[186:187], v[150:151], v[178:179]
	v_pk_mul_f32 v[180:181], v[170:171], v[188:189]
	v_pk_mul_f32 v[182:183], v[172:173], v[188:189]
	v_pk_mul_f32 v[184:185], v[176:177], v[188:189]
	v_pk_mul_f32 v[186:187], v[178:179], v[188:189]
	v_exp_f32_e32 v180, v180
	v_exp_f32_e32 v181, v181
	v_exp_f32_e32 v182, v182
	v_exp_f32_e32 v183, v183
	v_exp_f32_e32 v184, v184
	v_exp_f32_e32 v185, v185
	v_exp_f32_e32 v186, v186
	v_exp_f32_e32 v187, v187
	s_nop 0
	v_pk_add_f32 v[180:181], v[180:181], 1.0 op_sel_hi:[1,0]
	v_pk_add_f32 v[182:183], v[182:183], 1.0 op_sel_hi:[1,0]
	v_pk_add_f32 v[184:185], v[184:185], 1.0 op_sel_hi:[1,0]
	v_pk_add_f32 v[186:187], v[186:187], 1.0 op_sel_hi:[1,0]
	v_rcp_f32_e32 v180, v180
	v_rcp_f32_e32 v181, v181
	v_rcp_f32_e32 v182, v182
	v_rcp_f32_e32 v183, v183
	v_rcp_f32_e32 v184, v184
	v_rcp_f32_e32 v185, v185
	v_rcp_f32_e32 v186, v186
	v_rcp_f32_e32 v187, v187
	s_nop 0
	v_pk_mul_f32 v[138:139], v[170:171], v[180:181]
	v_pk_mul_f32 v[134:135], v[172:173], v[182:183]
	v_pk_mul_f32 v[114:115], v[176:177], v[184:185]
	v_pk_mul_f32 v[106:107], v[178:179], v[186:187]
	v_pk_mul_f32 v[138:139], v[138:139], v[130:131]
	v_pk_mul_f32 v[134:135], v[134:135], v[110:111]
	v_pk_mul_f32 v[114:115], v[114:115], v[102:103]
	v_pk_mul_f32 v[106:107], v[106:107], v[98:99]
	v_mov_b32_dpp v172, v92 row_ror:1 row_mask:0xf bank_mask:0xf
	v_mov_b32_dpp v176, v88 row_ror:1 row_mask:0xf bank_mask:0xf
	v_mov_b32_dpp v178, v80 row_ror:1 row_mask:0xf bank_mask:0xf
	v_mov_b32_dpp v180, v88 row_ror:15 row_mask:0xf bank_mask:0xf
	v_mov_b32_dpp v182, v80 row_ror:15 row_mask:0xf bank_mask:0xf
	v_mov_b32_dpp v184, v72 row_ror:15 row_mask:0xf bank_mask:0xf
	v_mov_b32_dpp v173, v93 row_ror:1 row_mask:0xf bank_mask:0xf
	v_mov_b32_dpp v177, v89 row_ror:1 row_mask:0xf bank_mask:0xf
	v_mov_b32_dpp v179, v81 row_ror:1 row_mask:0xf bank_mask:0xf
	v_mov_b32_dpp v181, v89 row_ror:15 row_mask:0xf bank_mask:0xf
	v_mov_b32_dpp v183, v81 row_ror:15 row_mask:0xf bank_mask:0xf
	v_mov_b32_dpp v185, v73 row_ror:15 row_mask:0xf bank_mask:0xf
	v_mov_b32_dpp v170, v92 row_shr:1 row_mask:0xf bank_mask:0xf bound_ctrl:1
	v_mov_b32_dpp v172, v88 row_shr:1 row_mask:0xf bank_mask:0xf
	v_mov_b32_dpp v176, v80 row_shr:1 row_mask:0xf bank_mask:0xf
	v_mov_b32_dpp v178, v72 row_shr:1 row_mask:0xf bank_mask:0xf
	v_mov_b32_dpp v180, v92 row_shl:1 row_mask:0xf bank_mask:0xf
	v_mov_b32_dpp v182, v88 row_shl:1 row_mask:0xf bank_mask:0xf
	v_mov_b32_dpp v184, v80 row_shl:1 row_mask:0xf bank_mask:0xf
	v_mov_b32_dpp v186, v72 row_shl:1 row_mask:0xf bank_mask:0xf bound_ctrl:1
	v_mov_b32_dpp v171, v93 row_shr:1 row_mask:0xf bank_mask:0xf bound_ctrl:1
	v_mov_b32_dpp v173, v89 row_shr:1 row_mask:0xf bank_mask:0xf
	v_mov_b32_dpp v177, v81 row_shr:1 row_mask:0xf bank_mask:0xf
	v_mov_b32_dpp v179, v73 row_shr:1 row_mask:0xf bank_mask:0xf
	v_mov_b32_dpp v181, v93 row_shl:1 row_mask:0xf bank_mask:0xf
	v_mov_b32_dpp v183, v89 row_shl:1 row_mask:0xf bank_mask:0xf
	v_mov_b32_dpp v185, v81 row_shl:1 row_mask:0xf bank_mask:0xf
	v_mov_b32_dpp v187, v73 row_shl:1 row_mask:0xf bank_mask:0xf bound_ctrl:1
	v_pk_fma_f32 v[170:171], v[170:171], v[140:141], v[124:125]
	v_pk_fma_f32 v[172:173], v[172:173], v[140:141], v[124:125]
	v_pk_fma_f32 v[176:177], v[176:177], v[140:141], v[124:125]
	v_pk_fma_f32 v[178:179], v[178:179], v[140:141], v[124:125]
	v_pk_fma_f32 v[170:171], v[92:93], v[116:117], v[170:171]
	v_pk_fma_f32 v[172:173], v[88:89], v[116:117], v[172:173]
	v_pk_fma_f32 v[176:177], v[80:81], v[116:117], v[176:177]
	v_pk_fma_f32 v[178:179], v[72:73], v[116:117], v[178:179]
	v_pk_fma_f32 v[170:171], v[180:181], v[120:121], v[170:171]
	v_pk_fma_f32 v[172:173], v[182:183], v[120:121], v[172:173]
	v_pk_fma_f32 v[176:177], v[184:185], v[120:121], v[176:177]
	v_pk_fma_f32 v[178:179], v[186:187], v[120:121], v[178:179]
	v_pk_mul_f32 v[180:181], v[170:171], v[188:189]
	v_pk_mul_f32 v[182:183], v[172:173], v[188:189]
	v_pk_mul_f32 v[184:185], v[176:177], v[188:189]
	v_pk_mul_f32 v[186:187], v[178:179], v[188:189]
	v_exp_f32_e32 v180, v180
	v_exp_f32_e32 v181, v181
	v_exp_f32_e32 v182, v182
	v_exp_f32_e32 v183, v183
	v_exp_f32_e32 v184, v184
	v_exp_f32_e32 v185, v185
	v_exp_f32_e32 v186, v186
	v_exp_f32_e32 v187, v187
	s_nop 0
	v_pk_add_f32 v[180:181], v[180:181], 1.0 op_sel_hi:[1,0]
	v_pk_add_f32 v[182:183], v[182:183], 1.0 op_sel_hi:[1,0]
	v_pk_add_f32 v[184:185], v[184:185], 1.0 op_sel_hi:[1,0]
	v_pk_add_f32 v[186:187], v[186:187], 1.0 op_sel_hi:[1,0]
	v_rcp_f32_e32 v180, v180
	v_rcp_f32_e32 v181, v181
	v_rcp_f32_e32 v182, v182
	v_rcp_f32_e32 v183, v183
	v_rcp_f32_e32 v184, v184
	v_rcp_f32_e32 v185, v185
	v_rcp_f32_e32 v186, v186
	v_rcp_f32_e32 v187, v187
	s_nop 0
	v_pk_mul_f32 v[92:93], v[170:171], v[180:181]
	v_pk_mul_f32 v[88:89], v[172:173], v[182:183]
	v_pk_mul_f32 v[80:81], v[176:177], v[184:185]
	v_pk_mul_f32 v[72:73], v[178:179], v[186:187]
	v_pk_mul_f32 v[92:93], v[92:93], v[84:85]
	v_pk_mul_f32 v[88:89], v[88:89], v[76:77]
	v_pk_mul_f32 v[80:81], v[80:81], v[68:69]
	v_pk_mul_f32 v[72:73], v[72:73], v[64:65]
	v_mov_b32_dpp v172, v94 row_ror:1 row_mask:0xf bank_mask:0xf
	v_mov_b32_dpp v176, v90 row_ror:1 row_mask:0xf bank_mask:0xf
	v_mov_b32_dpp v178, v82 row_ror:1 row_mask:0xf bank_mask:0xf
	v_mov_b32_dpp v180, v90 row_ror:15 row_mask:0xf bank_mask:0xf
	v_mov_b32_dpp v182, v82 row_ror:15 row_mask:0xf bank_mask:0xf
	v_mov_b32_dpp v184, v74 row_ror:15 row_mask:0xf bank_mask:0xf
	v_mov_b32_dpp v173, v95 row_ror:1 row_mask:0xf bank_mask:0xf
	v_mov_b32_dpp v177, v91 row_ror:1 row_mask:0xf bank_mask:0xf
	v_mov_b32_dpp v179, v83 row_ror:1 row_mask:0xf bank_mask:0xf
	v_mov_b32_dpp v181, v91 row_ror:15 row_mask:0xf bank_mask:0xf
	v_mov_b32_dpp v183, v83 row_ror:15 row_mask:0xf bank_mask:0xf
	v_mov_b32_dpp v185, v75 row_ror:15 row_mask:0xf bank_mask:0xf
	v_mov_b32_dpp v170, v94 row_shr:1 row_mask:0xf bank_mask:0xf bound_ctrl:1
	v_mov_b32_dpp v172, v90 row_shr:1 row_mask:0xf bank_mask:0xf
	v_mov_b32_dpp v176, v82 row_shr:1 row_mask:0xf bank_mask:0xf
	v_mov_b32_dpp v178, v74 row_shr:1 row_mask:0xf bank_mask:0xf
	v_mov_b32_dpp v180, v94 row_shl:1 row_mask:0xf bank_mask:0xf
	v_mov_b32_dpp v182, v90 row_shl:1 row_mask:0xf bank_mask:0xf
	v_mov_b32_dpp v184, v82 row_shl:1 row_mask:0xf bank_mask:0xf
	v_mov_b32_dpp v186, v74 row_shl:1 row_mask:0xf bank_mask:0xf bound_ctrl:1
	v_mov_b32_dpp v171, v95 row_shr:1 row_mask:0xf bank_mask:0xf bound_ctrl:1
	v_mov_b32_dpp v173, v91 row_shr:1 row_mask:0xf bank_mask:0xf
	v_mov_b32_dpp v177, v83 row_shr:1 row_mask:0xf bank_mask:0xf
	v_mov_b32_dpp v179, v75 row_shr:1 row_mask:0xf bank_mask:0xf
	v_mov_b32_dpp v181, v95 row_shl:1 row_mask:0xf bank_mask:0xf
	v_mov_b32_dpp v183, v91 row_shl:1 row_mask:0xf bank_mask:0xf
	v_mov_b32_dpp v185, v83 row_shl:1 row_mask:0xf bank_mask:0xf
	v_mov_b32_dpp v187, v75 row_shl:1 row_mask:0xf bank_mask:0xf bound_ctrl:1
	v_pk_fma_f32 v[170:171], v[170:171], v[142:143], v[126:127]
	v_pk_fma_f32 v[172:173], v[172:173], v[142:143], v[126:127]
	v_pk_fma_f32 v[176:177], v[176:177], v[142:143], v[126:127]
	v_pk_fma_f32 v[178:179], v[178:179], v[142:143], v[126:127]
	v_pk_fma_f32 v[170:171], v[94:95], v[118:119], v[170:171]
	v_pk_fma_f32 v[172:173], v[90:91], v[118:119], v[172:173]
	v_pk_fma_f32 v[176:177], v[82:83], v[118:119], v[176:177]
	v_pk_fma_f32 v[178:179], v[74:75], v[118:119], v[178:179]
	v_pk_fma_f32 v[170:171], v[180:181], v[122:123], v[170:171]
	v_pk_fma_f32 v[172:173], v[182:183], v[122:123], v[172:173]
	v_pk_fma_f32 v[176:177], v[184:185], v[122:123], v[176:177]
	v_pk_fma_f32 v[178:179], v[186:187], v[122:123], v[178:179]
	v_pk_mul_f32 v[180:181], v[170:171], v[188:189]
	v_pk_mul_f32 v[182:183], v[172:173], v[188:189]
	v_pk_mul_f32 v[184:185], v[176:177], v[188:189]
	v_pk_mul_f32 v[186:187], v[178:179], v[188:189]
	v_exp_f32_e32 v180, v180
	v_exp_f32_e32 v181, v181
	v_exp_f32_e32 v182, v182
	v_exp_f32_e32 v183, v183
	v_exp_f32_e32 v184, v184
	v_exp_f32_e32 v185, v185
	v_exp_f32_e32 v186, v186
	v_exp_f32_e32 v187, v187
	s_nop 0
	v_pk_add_f32 v[180:181], v[180:181], 1.0 op_sel_hi:[1,0]
	v_pk_add_f32 v[182:183], v[182:183], 1.0 op_sel_hi:[1,0]
	v_pk_add_f32 v[184:185], v[184:185], 1.0 op_sel_hi:[1,0]
	v_pk_add_f32 v[186:187], v[186:187], 1.0 op_sel_hi:[1,0]
	v_rcp_f32_e32 v180, v180
	v_rcp_f32_e32 v181, v181
	v_rcp_f32_e32 v182, v182
	v_rcp_f32_e32 v183, v183
	v_rcp_f32_e32 v184, v184
	v_rcp_f32_e32 v185, v185
	v_rcp_f32_e32 v186, v186
	v_rcp_f32_e32 v187, v187
	s_nop 0
	v_pk_mul_f32 v[94:95], v[170:171], v[180:181]
	v_pk_mul_f32 v[90:91], v[172:173], v[182:183]
	v_pk_mul_f32 v[82:83], v[176:177], v[184:185]
	v_pk_mul_f32 v[74:75], v[178:179], v[186:187]
	v_pk_mul_f32 v[94:95], v[94:95], v[86:87]
	v_pk_mul_f32 v[90:91], v[90:91], v[78:79]
	v_pk_mul_f32 v[82:83], v[82:83], v[70:71]
	v_pk_mul_f32 v[74:75], v[74:75], v[66:67]
	v_cvt_pk_bf16_f32 v128, v136, v137
	v_cvt_pk_bf16_f32 v129, v138, v139
	v_cvt_pk_bf16_f32 v130, v92, v93
	v_cvt_pk_bf16_f32 v131, v94, v95
	buffer_store_dwordx4 v[128:131], v194, s[24:27], 0 offen sc1
	v_cvt_pk_bf16_f32 v108, v132, v133
	v_cvt_pk_bf16_f32 v109, v134, v135
	v_cvt_pk_bf16_f32 v110, v88, v89
	v_cvt_pk_bf16_f32 v111, v90, v91
	v_add_u32_e32 v195, 0x16000, v194
	buffer_store_dwordx4 v[108:111], v195, s[24:27], 0 offen sc1
	v_cvt_pk_bf16_f32 v100, v112, v113
	v_cvt_pk_bf16_f32 v101, v114, v115
	v_cvt_pk_bf16_f32 v102, v80, v81
	v_cvt_pk_bf16_f32 v103, v82, v83
	v_add_u32_e32 v195, 0x2c000, v194
	buffer_store_dwordx4 v[100:103], v195, s[24:27], 0 offen sc1
	v_cvt_pk_bf16_f32 v96, v104, v105
	v_cvt_pk_bf16_f32 v97, v106, v107
	v_cvt_pk_bf16_f32 v98, v72, v73
	v_cvt_pk_bf16_f32 v99, v74, v75
	v_add_u32_e32 v195, 0x42000, v194
	buffer_store_dwordx4 v[96:99], v195, s[24:27], 0 offen sc1
	v_mov_b32_dpp v172, v60 row_ror:1 row_mask:0xf bank_mask:0xf
	v_mov_b32_dpp v176, v56 row_ror:1 row_mask:0xf bank_mask:0xf
	v_mov_b32_dpp v178, v48 row_ror:1 row_mask:0xf bank_mask:0xf
	v_mov_b32_dpp v180, v56 row_ror:15 row_mask:0xf bank_mask:0xf
	v_mov_b32_dpp v182, v48 row_ror:15 row_mask:0xf bank_mask:0xf
	v_mov_b32_dpp v184, v40 row_ror:15 row_mask:0xf bank_mask:0xf
	v_mov_b32_dpp v173, v61 row_ror:1 row_mask:0xf bank_mask:0xf
	v_mov_b32_dpp v177, v57 row_ror:1 row_mask:0xf bank_mask:0xf
	v_mov_b32_dpp v179, v49 row_ror:1 row_mask:0xf bank_mask:0xf
	v_mov_b32_dpp v181, v57 row_ror:15 row_mask:0xf bank_mask:0xf
	v_mov_b32_dpp v183, v49 row_ror:15 row_mask:0xf bank_mask:0xf
	v_mov_b32_dpp v185, v41 row_ror:15 row_mask:0xf bank_mask:0xf
	v_mov_b32_dpp v170, v60 row_shr:1 row_mask:0xf bank_mask:0xf bound_ctrl:1
	v_mov_b32_dpp v172, v56 row_shr:1 row_mask:0xf bank_mask:0xf
	v_mov_b32_dpp v176, v48 row_shr:1 row_mask:0xf bank_mask:0xf
	v_mov_b32_dpp v178, v40 row_shr:1 row_mask:0xf bank_mask:0xf
	v_mov_b32_dpp v180, v60 row_shl:1 row_mask:0xf bank_mask:0xf
	v_mov_b32_dpp v182, v56 row_shl:1 row_mask:0xf bank_mask:0xf
	v_mov_b32_dpp v184, v48 row_shl:1 row_mask:0xf bank_mask:0xf
	v_mov_b32_dpp v186, v40 row_shl:1 row_mask:0xf bank_mask:0xf bound_ctrl:1
	v_mov_b32_dpp v171, v61 row_shr:1 row_mask:0xf bank_mask:0xf bound_ctrl:1
	v_mov_b32_dpp v173, v57 row_shr:1 row_mask:0xf bank_mask:0xf
	v_mov_b32_dpp v177, v49 row_shr:1 row_mask:0xf bank_mask:0xf
	v_mov_b32_dpp v179, v41 row_shr:1 row_mask:0xf bank_mask:0xf
	v_mov_b32_dpp v181, v61 row_shl:1 row_mask:0xf bank_mask:0xf
	v_mov_b32_dpp v183, v57 row_shl:1 row_mask:0xf bank_mask:0xf
	v_mov_b32_dpp v185, v49 row_shl:1 row_mask:0xf bank_mask:0xf
	v_mov_b32_dpp v187, v41 row_shl:1 row_mask:0xf bank_mask:0xf bound_ctrl:1
	v_pk_fma_f32 v[170:171], v[170:171], v[156:157], v[152:153]
	v_pk_fma_f32 v[172:173], v[172:173], v[156:157], v[152:153]
	v_pk_fma_f32 v[176:177], v[176:177], v[156:157], v[152:153]
	v_pk_fma_f32 v[178:179], v[178:179], v[156:157], v[152:153]
	v_pk_fma_f32 v[170:171], v[60:61], v[144:145], v[170:171]
	v_pk_fma_f32 v[172:173], v[56:57], v[144:145], v[172:173]
	v_pk_fma_f32 v[176:177], v[48:49], v[144:145], v[176:177]
	v_pk_fma_f32 v[178:179], v[40:41], v[144:145], v[178:179]
	v_pk_fma_f32 v[170:171], v[180:181], v[148:149], v[170:171]
	v_pk_fma_f32 v[172:173], v[182:183], v[148:149], v[172:173]
	v_pk_fma_f32 v[176:177], v[184:185], v[148:149], v[176:177]
	v_pk_fma_f32 v[178:179], v[186:187], v[148:149], v[178:179]
	v_pk_mul_f32 v[180:181], v[170:171], v[188:189]
	v_pk_mul_f32 v[182:183], v[172:173], v[188:189]
	v_pk_mul_f32 v[184:185], v[176:177], v[188:189]
	v_pk_mul_f32 v[186:187], v[178:179], v[188:189]
	v_exp_f32_e32 v180, v180
	v_exp_f32_e32 v181, v181
	v_exp_f32_e32 v182, v182
	v_exp_f32_e32 v183, v183
	v_exp_f32_e32 v184, v184
	v_exp_f32_e32 v185, v185
	v_exp_f32_e32 v186, v186
	v_exp_f32_e32 v187, v187
	s_nop 0
	v_pk_add_f32 v[180:181], v[180:181], 1.0 op_sel_hi:[1,0]
	v_pk_add_f32 v[182:183], v[182:183], 1.0 op_sel_hi:[1,0]
	v_pk_add_f32 v[184:185], v[184:185], 1.0 op_sel_hi:[1,0]
	v_pk_add_f32 v[186:187], v[186:187], 1.0 op_sel_hi:[1,0]
	v_rcp_f32_e32 v180, v180
	v_rcp_f32_e32 v181, v181
	v_rcp_f32_e32 v182, v182
	v_rcp_f32_e32 v183, v183
	v_rcp_f32_e32 v184, v184
	v_rcp_f32_e32 v185, v185
	v_rcp_f32_e32 v186, v186
	v_rcp_f32_e32 v187, v187
	s_nop 0
	v_pk_mul_f32 v[60:61], v[170:171], v[180:181]
	v_pk_mul_f32 v[56:57], v[172:173], v[182:183]
	v_pk_mul_f32 v[48:49], v[176:177], v[184:185]
	v_pk_mul_f32 v[40:41], v[178:179], v[186:187]
	v_pk_mul_f32 v[60:61], v[60:61], v[52:53]
	v_pk_mul_f32 v[56:57], v[56:57], v[44:45]
	v_pk_mul_f32 v[48:49], v[48:49], v[36:37]
	v_pk_mul_f32 v[40:41], v[40:41], v[32:33]
	v_mov_b32_dpp v172, v62 row_ror:1 row_mask:0xf bank_mask:0xf
	v_mov_b32_dpp v176, v58 row_ror:1 row_mask:0xf bank_mask:0xf
	v_mov_b32_dpp v178, v50 row_ror:1 row_mask:0xf bank_mask:0xf
	v_mov_b32_dpp v180, v58 row_ror:15 row_mask:0xf bank_mask:0xf
	v_mov_b32_dpp v182, v50 row_ror:15 row_mask:0xf bank_mask:0xf
	v_mov_b32_dpp v184, v42 row_ror:15 row_mask:0xf bank_mask:0xf
	v_mov_b32_dpp v173, v63 row_ror:1 row_mask:0xf bank_mask:0xf
	v_mov_b32_dpp v177, v59 row_ror:1 row_mask:0xf bank_mask:0xf
	v_mov_b32_dpp v179, v51 row_ror:1 row_mask:0xf bank_mask:0xf
	v_mov_b32_dpp v181, v59 row_ror:15 row_mask:0xf bank_mask:0xf
	v_mov_b32_dpp v183, v51 row_ror:15 row_mask:0xf bank_mask:0xf
	v_mov_b32_dpp v185, v43 row_ror:15 row_mask:0xf bank_mask:0xf
	v_mov_b32_dpp v170, v62 row_shr:1 row_mask:0xf bank_mask:0xf bound_ctrl:1
	v_mov_b32_dpp v172, v58 row_shr:1 row_mask:0xf bank_mask:0xf
	v_mov_b32_dpp v176, v50 row_shr:1 row_mask:0xf bank_mask:0xf
	v_mov_b32_dpp v178, v42 row_shr:1 row_mask:0xf bank_mask:0xf
	v_mov_b32_dpp v180, v62 row_shl:1 row_mask:0xf bank_mask:0xf
	v_mov_b32_dpp v182, v58 row_shl:1 row_mask:0xf bank_mask:0xf
	v_mov_b32_dpp v184, v50 row_shl:1 row_mask:0xf bank_mask:0xf
	v_mov_b32_dpp v186, v42 row_shl:1 row_mask:0xf bank_mask:0xf bound_ctrl:1
	v_mov_b32_dpp v171, v63 row_shr:1 row_mask:0xf bank_mask:0xf bound_ctrl:1
	v_mov_b32_dpp v173, v59 row_shr:1 row_mask:0xf bank_mask:0xf
	v_mov_b32_dpp v177, v51 row_shr:1 row_mask:0xf bank_mask:0xf
	v_mov_b32_dpp v179, v43 row_shr:1 row_mask:0xf bank_mask:0xf
	v_mov_b32_dpp v181, v63 row_shl:1 row_mask:0xf bank_mask:0xf
	v_mov_b32_dpp v183, v59 row_shl:1 row_mask:0xf bank_mask:0xf
	v_mov_b32_dpp v185, v51 row_shl:1 row_mask:0xf bank_mask:0xf
	v_mov_b32_dpp v187, v43 row_shl:1 row_mask:0xf bank_mask:0xf bound_ctrl:1
	v_pk_fma_f32 v[170:171], v[170:171], v[158:159], v[154:155]
	v_pk_fma_f32 v[172:173], v[172:173], v[158:159], v[154:155]
	v_pk_fma_f32 v[176:177], v[176:177], v[158:159], v[154:155]
	v_pk_fma_f32 v[178:179], v[178:179], v[158:159], v[154:155]
	v_pk_fma_f32 v[170:171], v[62:63], v[146:147], v[170:171]
	v_pk_fma_f32 v[172:173], v[58:59], v[146:147], v[172:173]
	v_pk_fma_f32 v[176:177], v[50:51], v[146:147], v[176:177]
	v_pk_fma_f32 v[178:179], v[42:43], v[146:147], v[178:179]
	v_pk_fma_f32 v[170:171], v[180:181], v[150:151], v[170:171]
	v_pk_fma_f32 v[172:173], v[182:183], v[150:151], v[172:173]
	v_pk_fma_f32 v[176:177], v[184:185], v[150:151], v[176:177]
	v_pk_fma_f32 v[178:179], v[186:187], v[150:151], v[178:179]
	v_pk_mul_f32 v[180:181], v[170:171], v[188:189]
	v_pk_mul_f32 v[182:183], v[172:173], v[188:189]
	v_pk_mul_f32 v[184:185], v[176:177], v[188:189]
	v_pk_mul_f32 v[186:187], v[178:179], v[188:189]
	v_exp_f32_e32 v180, v180
	v_exp_f32_e32 v181, v181
	v_exp_f32_e32 v182, v182
	v_exp_f32_e32 v183, v183
	v_exp_f32_e32 v184, v184
	v_exp_f32_e32 v185, v185
	v_exp_f32_e32 v186, v186
	v_exp_f32_e32 v187, v187
	s_nop 0
	v_pk_add_f32 v[180:181], v[180:181], 1.0 op_sel_hi:[1,0]
	v_pk_add_f32 v[182:183], v[182:183], 1.0 op_sel_hi:[1,0]
	v_pk_add_f32 v[184:185], v[184:185], 1.0 op_sel_hi:[1,0]
	v_pk_add_f32 v[186:187], v[186:187], 1.0 op_sel_hi:[1,0]
	v_rcp_f32_e32 v180, v180
	v_rcp_f32_e32 v181, v181
	v_rcp_f32_e32 v182, v182
	v_rcp_f32_e32 v183, v183
	v_rcp_f32_e32 v184, v184
	v_rcp_f32_e32 v185, v185
	v_rcp_f32_e32 v186, v186
	v_rcp_f32_e32 v187, v187
	s_nop 0
	v_pk_mul_f32 v[62:63], v[170:171], v[180:181]
	v_pk_mul_f32 v[58:59], v[172:173], v[182:183]
	v_pk_mul_f32 v[50:51], v[176:177], v[184:185]
	v_pk_mul_f32 v[42:43], v[178:179], v[186:187]
	v_pk_mul_f32 v[62:63], v[62:63], v[54:55]
	v_pk_mul_f32 v[58:59], v[58:59], v[46:47]
	v_pk_mul_f32 v[50:51], v[50:51], v[38:39]
	v_pk_mul_f32 v[42:43], v[42:43], v[34:35]
	v_mov_b32_dpp v172, v28 row_ror:1 row_mask:0xf bank_mask:0xf
	v_mov_b32_dpp v176, v24 row_ror:1 row_mask:0xf bank_mask:0xf
	v_mov_b32_dpp v178, v16 row_ror:1 row_mask:0xf bank_mask:0xf
	v_mov_b32_dpp v180, v24 row_ror:15 row_mask:0xf bank_mask:0xf
	v_mov_b32_dpp v182, v16 row_ror:15 row_mask:0xf bank_mask:0xf
	v_mov_b32_dpp v184, v8 row_ror:15 row_mask:0xf bank_mask:0xf
	v_mov_b32_dpp v173, v29 row_ror:1 row_mask:0xf bank_mask:0xf
	v_mov_b32_dpp v177, v25 row_ror:1 row_mask:0xf bank_mask:0xf
	v_mov_b32_dpp v179, v17 row_ror:1 row_mask:0xf bank_mask:0xf
	v_mov_b32_dpp v181, v25 row_ror:15 row_mask:0xf bank_mask:0xf
	v_mov_b32_dpp v183, v17 row_ror:15 row_mask:0xf bank_mask:0xf
	v_mov_b32_dpp v185, v9 row_ror:15 row_mask:0xf bank_mask:0xf
	v_mov_b32_dpp v170, v28 row_shr:1 row_mask:0xf bank_mask:0xf bound_ctrl:1
	v_mov_b32_dpp v172, v24 row_shr:1 row_mask:0xf bank_mask:0xf
	v_mov_b32_dpp v176, v16 row_shr:1 row_mask:0xf bank_mask:0xf
	v_mov_b32_dpp v178, v8 row_shr:1 row_mask:0xf bank_mask:0xf
	v_mov_b32_dpp v180, v28 row_shl:1 row_mask:0xf bank_mask:0xf
	v_mov_b32_dpp v182, v24 row_shl:1 row_mask:0xf bank_mask:0xf
	v_mov_b32_dpp v184, v16 row_shl:1 row_mask:0xf bank_mask:0xf
	v_mov_b32_dpp v186, v8 row_shl:1 row_mask:0xf bank_mask:0xf bound_ctrl:1
	v_mov_b32_dpp v171, v29 row_shr:1 row_mask:0xf bank_mask:0xf bound_ctrl:1
	v_mov_b32_dpp v173, v25 row_shr:1 row_mask:0xf bank_mask:0xf
	v_mov_b32_dpp v177, v17 row_shr:1 row_mask:0xf bank_mask:0xf
	v_mov_b32_dpp v179, v9 row_shr:1 row_mask:0xf bank_mask:0xf
	v_mov_b32_dpp v181, v29 row_shl:1 row_mask:0xf bank_mask:0xf
	v_mov_b32_dpp v183, v25 row_shl:1 row_mask:0xf bank_mask:0xf
	v_mov_b32_dpp v185, v17 row_shl:1 row_mask:0xf bank_mask:0xf
	v_mov_b32_dpp v187, v9 row_shl:1 row_mask:0xf bank_mask:0xf bound_ctrl:1
	v_pk_fma_f32 v[170:171], v[170:171], v[140:141], v[124:125]
	v_pk_fma_f32 v[172:173], v[172:173], v[140:141], v[124:125]
	v_pk_fma_f32 v[176:177], v[176:177], v[140:141], v[124:125]
	v_pk_fma_f32 v[178:179], v[178:179], v[140:141], v[124:125]
	v_pk_fma_f32 v[170:171], v[28:29], v[116:117], v[170:171]
	v_pk_fma_f32 v[172:173], v[24:25], v[116:117], v[172:173]
	v_pk_fma_f32 v[176:177], v[16:17], v[116:117], v[176:177]
	v_pk_fma_f32 v[178:179], v[8:9], v[116:117], v[178:179]
	v_pk_fma_f32 v[170:171], v[180:181], v[120:121], v[170:171]
	v_pk_fma_f32 v[172:173], v[182:183], v[120:121], v[172:173]
	v_pk_fma_f32 v[176:177], v[184:185], v[120:121], v[176:177]
	v_pk_fma_f32 v[178:179], v[186:187], v[120:121], v[178:179]
	v_pk_mul_f32 v[180:181], v[170:171], v[188:189]
	v_pk_mul_f32 v[182:183], v[172:173], v[188:189]
	v_pk_mul_f32 v[184:185], v[176:177], v[188:189]
	v_pk_mul_f32 v[186:187], v[178:179], v[188:189]
	v_exp_f32_e32 v180, v180
	v_exp_f32_e32 v181, v181
	v_exp_f32_e32 v182, v182
	v_exp_f32_e32 v183, v183
	v_exp_f32_e32 v184, v184
	v_exp_f32_e32 v185, v185
	v_exp_f32_e32 v186, v186
	v_exp_f32_e32 v187, v187
	s_nop 0
	v_pk_add_f32 v[180:181], v[180:181], 1.0 op_sel_hi:[1,0]
	v_pk_add_f32 v[182:183], v[182:183], 1.0 op_sel_hi:[1,0]
	v_pk_add_f32 v[184:185], v[184:185], 1.0 op_sel_hi:[1,0]
	v_pk_add_f32 v[186:187], v[186:187], 1.0 op_sel_hi:[1,0]
	v_rcp_f32_e32 v180, v180
	v_rcp_f32_e32 v181, v181
	v_rcp_f32_e32 v182, v182
	v_rcp_f32_e32 v183, v183
	v_rcp_f32_e32 v184, v184
	v_rcp_f32_e32 v185, v185
	v_rcp_f32_e32 v186, v186
	v_rcp_f32_e32 v187, v187
	s_nop 0
	v_pk_mul_f32 v[28:29], v[170:171], v[180:181]
	v_pk_mul_f32 v[24:25], v[172:173], v[182:183]
	v_pk_mul_f32 v[16:17], v[176:177], v[184:185]
	v_pk_mul_f32 v[8:9], v[178:179], v[186:187]
	v_pk_mul_f32 v[28:29], v[28:29], v[20:21]
	v_pk_mul_f32 v[24:25], v[24:25], v[12:13]
	v_pk_mul_f32 v[16:17], v[16:17], v[4:5]
	v_pk_mul_f32 v[8:9], v[8:9], v[0:1]
	v_mov_b32_dpp v172, v30 row_ror:1 row_mask:0xf bank_mask:0xf
	v_mov_b32_dpp v176, v26 row_ror:1 row_mask:0xf bank_mask:0xf
	v_mov_b32_dpp v178, v18 row_ror:1 row_mask:0xf bank_mask:0xf
	v_mov_b32_dpp v180, v26 row_ror:15 row_mask:0xf bank_mask:0xf
	v_mov_b32_dpp v182, v18 row_ror:15 row_mask:0xf bank_mask:0xf
	v_mov_b32_dpp v184, v10 row_ror:15 row_mask:0xf bank_mask:0xf
	v_mov_b32_dpp v173, v31 row_ror:1 row_mask:0xf bank_mask:0xf
	v_mov_b32_dpp v177, v27 row_ror:1 row_mask:0xf bank_mask:0xf
	v_mov_b32_dpp v179, v19 row_ror:1 row_mask:0xf bank_mask:0xf
	v_mov_b32_dpp v181, v27 row_ror:15 row_mask:0xf bank_mask:0xf
	v_mov_b32_dpp v183, v19 row_ror:15 row_mask:0xf bank_mask:0xf
	v_mov_b32_dpp v185, v11 row_ror:15 row_mask:0xf bank_mask:0xf
	v_mov_b32_dpp v170, v30 row_shr:1 row_mask:0xf bank_mask:0xf bound_ctrl:1
	v_mov_b32_dpp v172, v26 row_shr:1 row_mask:0xf bank_mask:0xf
	v_mov_b32_dpp v176, v18 row_shr:1 row_mask:0xf bank_mask:0xf
	v_mov_b32_dpp v178, v10 row_shr:1 row_mask:0xf bank_mask:0xf
	v_mov_b32_dpp v180, v30 row_shl:1 row_mask:0xf bank_mask:0xf
	v_mov_b32_dpp v182, v26 row_shl:1 row_mask:0xf bank_mask:0xf
	v_mov_b32_dpp v184, v18 row_shl:1 row_mask:0xf bank_mask:0xf
	v_mov_b32_dpp v186, v10 row_shl:1 row_mask:0xf bank_mask:0xf bound_ctrl:1
	v_mov_b32_dpp v171, v31 row_shr:1 row_mask:0xf bank_mask:0xf bound_ctrl:1
	v_mov_b32_dpp v173, v27 row_shr:1 row_mask:0xf bank_mask:0xf
	v_mov_b32_dpp v177, v19 row_shr:1 row_mask:0xf bank_mask:0xf
	v_mov_b32_dpp v179, v11 row_shr:1 row_mask:0xf bank_mask:0xf
	v_mov_b32_dpp v181, v31 row_shl:1 row_mask:0xf bank_mask:0xf
	v_mov_b32_dpp v183, v27 row_shl:1 row_mask:0xf bank_mask:0xf
	v_mov_b32_dpp v185, v19 row_shl:1 row_mask:0xf bank_mask:0xf
	v_mov_b32_dpp v187, v11 row_shl:1 row_mask:0xf bank_mask:0xf bound_ctrl:1
	v_pk_fma_f32 v[170:171], v[170:171], v[142:143], v[126:127]
	v_pk_fma_f32 v[172:173], v[172:173], v[142:143], v[126:127]
	v_pk_fma_f32 v[176:177], v[176:177], v[142:143], v[126:127]
	v_pk_fma_f32 v[178:179], v[178:179], v[142:143], v[126:127]
	v_pk_fma_f32 v[170:171], v[30:31], v[118:119], v[170:171]
	v_pk_fma_f32 v[172:173], v[26:27], v[118:119], v[172:173]
	v_pk_fma_f32 v[176:177], v[18:19], v[118:119], v[176:177]
	v_pk_fma_f32 v[178:179], v[10:11], v[118:119], v[178:179]
	v_pk_fma_f32 v[170:171], v[180:181], v[122:123], v[170:171]
	v_pk_fma_f32 v[172:173], v[182:183], v[122:123], v[172:173]
	v_pk_fma_f32 v[176:177], v[184:185], v[122:123], v[176:177]
	v_pk_fma_f32 v[178:179], v[186:187], v[122:123], v[178:179]
	v_pk_mul_f32 v[180:181], v[170:171], v[188:189]
	v_pk_mul_f32 v[182:183], v[172:173], v[188:189]
	v_pk_mul_f32 v[184:185], v[176:177], v[188:189]
	v_pk_mul_f32 v[186:187], v[178:179], v[188:189]
	v_exp_f32_e32 v180, v180
	v_exp_f32_e32 v181, v181
	v_exp_f32_e32 v182, v182
	v_exp_f32_e32 v183, v183
	v_exp_f32_e32 v184, v184
	v_exp_f32_e32 v185, v185
	v_exp_f32_e32 v186, v186
	v_exp_f32_e32 v187, v187
	s_nop 0
	v_pk_add_f32 v[180:181], v[180:181], 1.0 op_sel_hi:[1,0]
	v_pk_add_f32 v[182:183], v[182:183], 1.0 op_sel_hi:[1,0]
	v_pk_add_f32 v[184:185], v[184:185], 1.0 op_sel_hi:[1,0]
	v_pk_add_f32 v[186:187], v[186:187], 1.0 op_sel_hi:[1,0]
	v_rcp_f32_e32 v180, v180
	v_rcp_f32_e32 v181, v181
	v_rcp_f32_e32 v182, v182
	v_rcp_f32_e32 v183, v183
	v_rcp_f32_e32 v184, v184
	v_rcp_f32_e32 v185, v185
	v_rcp_f32_e32 v186, v186
	v_rcp_f32_e32 v187, v187
	s_nop 0
	v_pk_mul_f32 v[30:31], v[170:171], v[180:181]
	v_pk_mul_f32 v[26:27], v[172:173], v[182:183]
	v_pk_mul_f32 v[18:19], v[176:177], v[184:185]
	v_pk_mul_f32 v[10:11], v[178:179], v[186:187]
	v_pk_mul_f32 v[30:31], v[30:31], v[22:23]
	v_pk_mul_f32 v[26:27], v[26:27], v[14:15]
	v_pk_mul_f32 v[18:19], v[18:19], v[6:7]
	v_pk_mul_f32 v[10:11], v[10:11], v[2:3]
	v_cvt_pk_bf16_f32 v52, v60, v61
	v_cvt_pk_bf16_f32 v53, v62, v63
	v_cvt_pk_bf16_f32 v54, v28, v29
	v_cvt_pk_bf16_f32 v55, v30, v31
	v_add_u32_e32 v195, 0xb0000, v194
	buffer_store_dwordx4 v[52:55], v195, s[24:27], 0 offen sc1
	v_cvt_pk_bf16_f32 v44, v56, v57
	v_cvt_pk_bf16_f32 v45, v58, v59
	v_cvt_pk_bf16_f32 v46, v24, v25
	v_cvt_pk_bf16_f32 v47, v26, v27
	v_add_u32_e32 v195, 0xc6000, v194
	buffer_store_dwordx4 v[44:47], v195, s[24:27], 0 offen sc1
	v_cvt_pk_bf16_f32 v36, v48, v49
	v_cvt_pk_bf16_f32 v37, v50, v51
	v_cvt_pk_bf16_f32 v38, v16, v17
	v_cvt_pk_bf16_f32 v39, v18, v19
	v_add_u32_e32 v195, 0xdc000, v194
	buffer_store_dwordx4 v[36:39], v195, s[24:27], 0 offen sc1
	v_cvt_pk_bf16_f32 v32, v40, v41
	v_cvt_pk_bf16_f32 v33, v42, v43
	v_cvt_pk_bf16_f32 v34, v8, v9
	v_cvt_pk_bf16_f32 v35, v10, v11
	v_add_u32_e32 v195, 0xf2000, v194
	buffer_store_dwordx4 v[32:35], v195, s[24:27], 0 offen sc1
	s_mov_b64 s[24:25], -1
	s_cbranch_vccnz .LBB0_775
	s_andn2_b64 vcc, exec, s[8:9]
	s_cbranch_vccnz .LBB0_774
	s_barrier
	s_branch .LBB0_774
